# cross-attention phase: K/V LDS ring 2->4 stages, DMA issued two steps ahead with counted vmcnt(4) at the step barrier (on top of epilogue edits)
# baseline (speedup 1.0000x reference)
; #define LAS __attribute__((address_space(3)))
; template <int NKI, int NS, bool BAND> ...
;     ...
;     ATT_ISSUE(0, 0);
;     bf16x8 qf[8 * NKI];
;     if (active) { const bf16_t* qp = Qg + (size_t)(qb * 32 + l31) * 1024 + col0 + 8 * hi;
; #pragma unroll
;         for (int i = 0; i < 8 * NKI; ++i) qf[i] = *(const bf16x8*)(qp + 16 * i); }
;     else {
; #pragma unroll
;         for (int i = 0; i < 8 * NKI; ++i) qf[i] = (bf16x8){0, 0, 0, 0, 0, 0, 0, 0}; }
;     const int fl = ((l31 & 3) << 2) | ((l31 >> 2) & 3);
;     int koff[8];
; #pragma unroll
;     for (int s8 = 0; s8 < 8; ++s8) koff[s8] = 256 * l31 + (((2 * s8 + hi) ^ fl) << 4);
;     const int q4 = (lane & 15) >> 2, blk = (lane >> 4) & 1, p4 = lane & 3;
;     int voff[2][4];
; #pragma unroll
;     for (int t = 0; t < 2; ++t)
; #pragma unroll
;         for (int c = 0; c < 4; ++c) voff[t][c] = 256 * (4 * hi + 8 * t + q4) + ((((c ^ q4) << 2) | ((2 * blk + (p4 >> 1)) ^ ((hi + 2 * t) & 3))) << 4) + 8 * (p4 & 1);
;     f32x16 o[4];
; #pragma unroll
;     for (int c = 0; c < 4; ++c)
; #pragma unroll
;         for (int r = 0; r < 16; ++r) o[c][r] = 0.f;
;     float lsum = 0.f;
;     const LAS float* tb = btab + (head0 + s) * 264;
;     const float cfar = BAND ? tb[256] : cinit;
;     asm volatile("s_waitcnt vmcnt(0) lgkmcnt(0)" ::: "memory"); __builtin_amdgcn_s_barrier(); asm volatile("" ::: "memory");
;     for (int j = 0; j < nsteps; ++j) {
;         if (j + 1 < nsteps) ATT_ISSUE(j + 1, (j + 1) & 1);
.LBB0_969:
	v_add_u32_e32 v16, s38, v187
	s_lshl_b32 s39, s3, 1
	v_lshlrev_b64 v[20:21], 11, v[16:17]
	s_and_b32 s39, s39, 0x600
	v_lshl_add_u64 v[20:21], s[4:5], 0, v[20:21]
	v_or_b32_e32 v16, s39, v20
	v_readlane_b32 s48, v243, 39
	s_waitcnt vmcnt(0) lgkmcnt(0)
	s_barrier
	v_or_b32_e32 v20, v16, v18
	v_readlane_b32 s62, v243, 53
	v_readlane_b32 s63, v243, 54
	v_mov_b32_e32 v30, v17
	v_mov_b32_e32 v31, v17
	s_and_b32 s42, s43, 1
	v_lshl_add_u64 v[184:185], s[62:63], 0, v[20:21]
	s_mov_b64 s[98:99], 0x10000
	v_lshl_add_u64 v[18:19], v[184:185], 0, s[14:15]
	s_add_i32 m0, s44, 0x8000
	s_nop 0
	global_load_lds_dwordx4 v[18:19], off
	v_lshl_add_u64 v[18:19], v[184:185], 0, s[16:17]
	s_add_i32 m0, s44, 0xc000
	s_nop 0
	global_load_lds_dwordx4 v[18:19], off
	v_lshl_add_u64 v[18:19], v[184:185], 0, s[20:21]
	s_add_i32 m0, s44, 0xa000
	s_nop 0
	global_load_lds_dwordx4 v[18:19], off
	v_lshl_add_u64 v[18:19], v[184:185], 0, s[22:23]
	s_add_i32 m0, s44, 0xe000
	s_nop 0
	global_load_lds_dwordx4 v[18:19], off
	v_lshl_add_u64 v[184:185], v[184:185], 0, s[98:99]
	v_mov_b32_e32 v16, v17
	v_mov_b32_e32 v18, v17
	v_mov_b32_e32 v19, v17
	v_mov_b32_e32 v20, v17
	v_mov_b32_e32 v21, v17
	v_mov_b32_e32 v22, v17
	v_mov_b32_e32 v23, v17
	v_mov_b32_e32 v24, v17
	v_mov_b32_e32 v25, v17
	v_mov_b32_e32 v26, v17
	v_mov_b32_e32 v27, v17
	v_mov_b32_e32 v28, v17
	v_mov_b32_e32 v29, v17
	v_mov_b64_e32 v[46:47], v[30:31]
	v_mov_b64_e32 v[62:63], v[30:31]
	v_mov_b64_e32 v[78:79], v[30:31]
	v_mov_b64_e32 v[94:95], v[30:31]
	s_lshl_b32 s45, s42, 13
	s_mov_b32 s47, 0
	v_mov_b32_e32 v181, 0
	s_mov_b64 s[38:39], 0
	v_mov_b64_e32 v[44:45], v[28:29]
	v_mov_b64_e32 v[42:43], v[26:27]
	v_mov_b64_e32 v[40:41], v[24:25]
	v_mov_b64_e32 v[38:39], v[22:23]
	v_mov_b64_e32 v[36:37], v[20:21]
	v_mov_b64_e32 v[34:35], v[18:19]
	v_mov_b64_e32 v[32:33], v[16:17]
	v_mov_b64_e32 v[60:61], v[28:29]
	v_mov_b64_e32 v[58:59], v[26:27]
	v_mov_b64_e32 v[56:57], v[24:25]
	v_mov_b64_e32 v[54:55], v[22:23]
	v_mov_b64_e32 v[52:53], v[20:21]
	v_mov_b64_e32 v[50:51], v[18:19]
	v_mov_b64_e32 v[48:49], v[16:17]
	v_mov_b64_e32 v[76:77], v[28:29]
	v_mov_b64_e32 v[74:75], v[26:27]
	v_mov_b64_e32 v[72:73], v[24:25]
	v_mov_b64_e32 v[70:71], v[22:23]
	v_mov_b64_e32 v[68:69], v[20:21]
	v_mov_b64_e32 v[66:67], v[18:19]
	v_mov_b64_e32 v[64:65], v[16:17]
	v_mov_b64_e32 v[92:93], v[28:29]
	v_mov_b64_e32 v[90:91], v[26:27]
	v_mov_b64_e32 v[88:89], v[24:25]
	v_mov_b64_e32 v[86:87], v[22:23]
	v_mov_b64_e32 v[84:85], v[20:21]
	v_mov_b64_e32 v[82:83], v[18:19]
	v_mov_b64_e32 v[80:81], v[16:17]
	v_readlane_b32 s49, v243, 40
	v_readlane_b32 s50, v243, 41
	v_readlane_b32 s51, v243, 42
	v_readlane_b32 s52, v243, 43
	v_readlane_b32 s53, v243, 44
	v_readlane_b32 s54, v243, 45
	v_readlane_b32 s55, v243, 46
	v_readlane_b32 s56, v243, 47
	v_readlane_b32 s57, v243, 48
	v_readlane_b32 s58, v243, 49
	v_readlane_b32 s59, v243, 50
	v_readlane_b32 s60, v243, 51
	v_readlane_b32 s61, v243, 52
	s_waitcnt vmcnt(4)
.LBB0_970:
	s_add_i32 s46, s47, 0x8000
	v_cndmask_b32_e64 v16, 0, 1, s[36:37]
	s_cmp_gt_u32 s38, 0x50000
	s_cbranch_scc1 .Lp6_noissue
	s_add_i32 s4, s47, 0x10000
	s_and_b32 s4, s4, 0x18000
	s_add_i32 s4, s44, s4
	v_lshl_add_u64 v[18:19], v[184:185], 0, s[38:39]
	v_lshl_add_u64 v[20:21], v[18:19], 0, s[14:15]
	s_mov_b32 m0, s4
	s_nop 0
	global_load_lds_dwordx4 v[20:21], off
	v_lshl_add_u64 v[20:21], v[18:19], 0, s[16:17]
	s_add_i32 m0, s4, 0x4000
	s_nop 0
	global_load_lds_dwordx4 v[20:21], off
	v_lshl_add_u64 v[20:21], v[18:19], 0, s[20:21]
	s_add_i32 m0, s4, 0x2000
	v_lshl_add_u64 v[18:19], v[18:19], 0, s[22:23]
	global_load_lds_dwordx4 v[20:21], off
	s_add_i32 m0, s4, 0x6000
	s_nop 0
	global_load_lds_dwordx4 v[18:19], off
; template <int NKI, int NS, bool BAND> ...
;     ...
;         if (active) {
;             const LAS unsigned char* st = lds + (j & 1) * STG;
;             const LAS unsigned char* Kt = st + (s * 2 * NKI) * TILE; const LAS unsigned char* Vt = st + (s * 2 * NKI + NKI + dsel) * TILE;
;             f32x16 sc;
;             bool nearb = false;
;             if (BAND) { const int kcrel = crel0 - (j >> 1); nearb = kcrel < 3;
;                 if (nearb) { const int dbase = 64 * kcrel - 32 * (j & 1) + qb * 32 + l31 - 4 * hi;
; #pragma unroll
;                     for (int r = 0; r < 16; ++r) { int d = dbase - ((r & 3) + 8 * (r >> 2)); d = d > 128 ? 128 : d; sc[r] = tb[d + 128]; } } }
;             if (!nearb) {
; #pragma unroll
;                 for (int r = 0; r < 16; ++r) sc[r] = cfar; }
; #pragma unroll
;             for (int i = 0; i < NKI; ++i) {
;                 bf16x8 kf[8];
; #pragma unroll
;                 for (int s8 = 0; s8 < 8; ++s8) kf[s8] = *(const LAS bf16x8*)(Kt + i * TILE + koff[s8]);
;                 asm volatile("s_waitcnt lgkmcnt(0)" : "+v"(kf[0]), "+v"(kf[1]), "+v"(kf[2]), "+v"(kf[3]), "+v"(kf[4]), "+v"(kf[5]), "+v"(kf[6]), "+v"(kf[7]) :: "memory");
; #pragma unroll
;                 for (int s8 = 0; s8 < 8; ++s8) sc = __builtin_amdgcn_mfma_f32_32x32x16_bf16(kf[s8], qf[i * 8 + s8], sc, 0, 0, 0);
;             }
;             s16x4 va[8], vb[8];
;             { const unsigned sb = (unsigned)(size_t)Vt; VTR8(va, sb + voff[0][0], sb + voff[1][0], sb + voff[0][1], sb + voff[1][1]); VTR8(vb, sb + voff[0][2], sb + voff[1][2], sb + voff[0][3], sb + voff[1][3]); }
;             float pe[16];
; #pragma unroll
;             for (int r = 0; r < 16; ++r) { pe[r] = __builtin_amdgcn_exp2f(sc[r]); lsum += pe[r]; }
;             u32x4 pw0, pw1;
;             pw0.x = cvtpk(pe[0], pe[1]); pw0.y = cvtpk(pe[2], pe[3]); pw0.z = cvtpk(pe[4], pe[5]); pw0.w = cvtpk(pe[6], pe[7]);
;             pw1.x = cvtpk(pe[8], pe[9]); pw1.y = cvtpk(pe[10], pe[11]); pw1.z = cvtpk(pe[12], pe[13]); pw1.w = cvtpk(pe[14], pe[15]);
;             VTRW(8, va, pw0, pw1);
;             const bf16x8 pa0 = __builtin_bit_cast(bf16x8, pw0), pa1 = __builtin_bit_cast(bf16x8, pw1);
;             o[0] = __builtin_amdgcn_mfma_f32_32x32x16_bf16(pa0, VFR2(va[0], va[1]), o[0], 0, 0, 0); o[0] = __builtin_amdgcn_mfma_f32_32x32x16_bf16(pa1, VFR2(va[2], va[3]), o[0], 0, 0, 0);
.Lp6_noissue:
	s_andn2_b64 vcc, exec, s[36:37]
	v_cmp_ne_u32_e64 s[4:5], 1, v16
	s_cbranch_vccnz .LBB0_972
	s_and_b32 s47, s47, 0x18000
	s_add_i32 s47, s47, 0
	v_add_u32_e32 v237, s47, v197
	v_add_u32_e32 v16, s47, v190
	v_add_u32_e32 v30, s47, v191
	v_add_u32_e32 v31, s47, v192
	v_add_u32_e32 v183, s47, v193
	v_add_u32_e32 v234, s47, v194
	v_add_u32_e32 v235, s47, v195
	v_add_u32_e32 v236, s47, v196
	ds_read_b128 v[18:21], v237
	ds_read_b128 v[22:25], v236
	ds_read_b128 v[26:29], v235
	ds_read_b128 v[214:217], v234
	ds_read_b128 v[218:221], v183
	ds_read_b128 v[222:225], v31
	ds_read_b128 v[226:229], v30
	ds_read_b128 v[230:233], v16
	s_waitcnt lgkmcnt(0)
	s_waitcnt lgkmcnt(0)
	s_nop 0
	v_mfma_f32_32x32x16_bf16 v[96:111], v[230:233], v[112:115], v[0:15]
	s_add_i32 s47, s47, s45
	s_addk_i32 s47, 0x4000
	v_add_u32_e32 v238, s47, v201
	v_add_u32_e32 v239, s47, v205
	v_add_u32_e32 v240, s47, v202
	v_add_u32_e32 v241, s47, v206
	v_mfma_f32_32x32x16_bf16 v[96:111], v[226:229], v[116:119], v[96:111]
	v_mfma_f32_32x32x16_bf16 v[96:111], v[222:225], v[120:123], v[96:111]
	v_mfma_f32_32x32x16_bf16 v[96:111], v[218:221], v[128:131], v[96:111]
	v_mfma_f32_32x32x16_bf16 v[96:111], v[214:217], v[136:139], v[96:111]
	v_mfma_f32_32x32x16_bf16 v[96:111], v[26:29], v[152:155], v[96:111]
	v_mfma_f32_32x32x16_bf16 v[96:111], v[22:25], v[164:167], v[96:111]
	ds_read_b128 v[22:25], v237 offset:8192
	ds_read_b128 v[26:29], v236 offset:8192
	ds_read_b128 v[214:217], v235 offset:8192
	ds_read_b128 v[218:221], v234 offset:8192
	ds_read_b128 v[222:225], v183 offset:8192
	ds_read_b128 v[226:229], v31 offset:8192
	v_add_u32_e32 v31, s47, v200
	v_add_u32_e32 v183, s47, v204
	v_mfma_f32_32x32x16_bf16 v[96:111], v[18:21], v[148:151], v[96:111]
	ds_read_b128 v[18:21], v30 offset:8192
	ds_read_b128 v[230:233], v16 offset:8192
	s_waitcnt lgkmcnt(0)
	s_waitcnt lgkmcnt(0)
	v_add_u32_e32 v16, s47, v199
	v_mfma_f32_32x32x16_bf16 v[96:111], v[230:233], v[124:127], v[96:111]
	v_add_u32_e32 v30, s47, v203
	v_mfma_f32_32x32x16_bf16 v[96:111], v[18:21], v[132:135], v[96:111]
	v_mfma_f32_32x32x16_bf16 v[96:111], v[226:229], v[140:143], v[96:111]
	v_mfma_f32_32x32x16_bf16 v[96:111], v[222:225], v[156:159], v[96:111]
	v_mfma_f32_32x32x16_bf16 v[96:111], v[218:221], v[168:171], v[96:111]
	v_mfma_f32_32x32x16_bf16 v[96:111], v[214:217], v[172:175], v[96:111]
	v_mfma_f32_32x32x16_bf16 v[96:111], v[26:29], v[160:163], v[96:111]
	ds_read_b64_tr_b16 v[218:219], v16
	ds_read_b64_tr_b16 v[220:221], v30
	ds_read_b64_tr_b16 v[214:215], v16 offset:4096
	ds_read_b64_tr_b16 v[216:217], v30 offset:4096
	ds_read_b64_tr_b16 v[26:27], v31
	ds_read_b64_tr_b16 v[28:29], v183
	ds_read_b64_tr_b16 v[18:19], v31 offset:4096
	ds_read_b64_tr_b16 v[20:21], v183 offset:4096
	ds_read_b64_tr_b16 v[234:235], v238
	ds_read_b64_tr_b16 v[236:237], v239
	ds_read_b64_tr_b16 v[230:231], v238 offset:4096
	ds_read_b64_tr_b16 v[232:233], v239 offset:4096
	ds_read_b64_tr_b16 v[226:227], v240
	ds_read_b64_tr_b16 v[228:229], v241
	ds_read_b64_tr_b16 v[222:223], v240 offset:4096
	ds_read_b64_tr_b16 v[224:225], v241 offset:4096
	v_mfma_f32_32x32x16_bf16 v[96:111], v[22:25], v[144:147], v[96:111]
	s_nop 11
	v_exp_f32_e32 v16, v96
	v_exp_f32_e32 v30, v97
	v_exp_f32_e32 v31, v98
	v_exp_f32_e32 v183, v99
	v_exp_f32_e32 v100, v100
	v_exp_f32_e32 v101, v101
	v_exp_f32_e32 v102, v102
	v_exp_f32_e32 v103, v103
	v_exp_f32_e32 v104, v104
	v_exp_f32_e32 v105, v105
	v_exp_f32_e32 v106, v106
	v_exp_f32_e32 v107, v107
	v_exp_f32_e32 v108, v108
	v_exp_f32_e32 v109, v109
	v_exp_f32_e32 v110, v110
	v_exp_f32_e32 v111, v111
	v_cvt_pk_bf16_f32 v22, v16, v30
	v_cvt_pk_bf16_f32 v23, v31, v183
	v_cvt_pk_bf16_f32 v24, v100, v101
	v_cvt_pk_bf16_f32 v25, v102, v103
	v_cvt_pk_bf16_f32 v96, v104, v105
	v_cvt_pk_bf16_f32 v97, v106, v107
	v_cvt_pk_bf16_f32 v98, v108, v109
	v_cvt_pk_bf16_f32 v99, v110, v111
	s_waitcnt lgkmcnt(8)
	v_add_f32_e32 v16, v181, v16
	v_mfma_f32_32x32x16_bf16 v[64:79], v[22:25], v[26:29], v[64:79]
	v_mov_b64_e32 v[26:27], v[96:97]
	v_mov_b64_e32 v[28:29], v[98:99]
	v_add_f32_e32 v16, v30, v16
	v_add_f32_e32 v16, v31, v16
	v_add_f32_e32 v16, v183, v16
	v_add_f32_e32 v16, v100, v16
	v_add_f32_e32 v16, v101, v16
	v_mfma_f32_32x32x16_bf16 v[64:79], v[96:99], v[18:21], v[64:79]
	v_mov_b64_e32 v[18:19], v[22:23]
	v_mov_b64_e32 v[20:21], v[24:25]
	s_waitcnt lgkmcnt(0)
	v_add_f32_e32 v16, v102, v16
	v_add_f32_e32 v16, v103, v16
	v_add_f32_e32 v16, v104, v16
	v_add_f32_e32 v16, v105, v16
	v_mfma_f32_32x32x16_bf16 v[80:95], v[22:25], v[218:221], v[80:95]
	v_add_f32_e32 v16, v106, v16
	v_add_f32_e32 v16, v107, v16
	v_add_f32_e32 v16, v108, v16
	v_add_f32_e32 v16, v109, v16
	v_add_f32_e32 v16, v110, v16
	v_add_f32_e32 v181, v111, v16
	v_mfma_f32_32x32x16_bf16 v[48:63], v[22:25], v[234:237], v[48:63]
	v_mfma_f32_32x32x16_bf16 v[32:47], v[22:25], v[226:229], v[32:47]
	v_mfma_f32_32x32x16_bf16 v[80:95], v[96:99], v[214:217], v[80:95]
	v_mfma_f32_32x32x16_bf16 v[48:63], v[96:99], v[230:233], v[48:63]
	v_mfma_f32_32x32x16_bf16 v[32:47], v[96:99], v[222:225], v[32:47]
.LBB0_972:
	s_cmp_gt_u32 s38, 0x50000
	s_cbranch_scc1 .Lp6_w0
	s_waitcnt vmcnt(4) lgkmcnt(0)
	s_branch .Lp6_wd

; template <int NKI, int NS, bool BAND> ...
;     ...
;             for (int i = 0; i < NKI; ++i) {
;                 bf16x8 kf[8];
; #pragma unroll
;                 for (int s8 = 0; s8 < 8; ++s8) kf[s8] = *(const LAS bf16x8*)(Kt + i * TILE + koff[s8]);
;                 asm volatile("s_waitcnt lgkmcnt(0)" : "+v"(kf[0]), "+v"(kf[1]), "+v"(kf[2]), "+v"(kf[3]), "+v"(kf[4]), "+v"(kf[5]), "+v"(kf[6]), "+v"(kf[7]) :: "memory");
; #pragma unroll
;                 for (int s8 = 0; s8 < 8; ++s8) sc = __builtin_amdgcn_mfma_f32_32x32x16_bf16(kf[s8], qf[i * 8 + s8], sc, 0, 0, 0);
;             }
;             s16x4 va[8], vb[8];
;             { const unsigned sb = (unsigned)(size_t)Vt; VTR8(va, sb + voff[0][0], sb + voff[1][0], sb + voff[0][1], sb + voff[1][1]); VTR8(vb, sb + voff[0][2], sb + voff[1][2], sb + voff[0][3], sb + voff[1][3]); }
;             float pe[16];
; #pragma unroll
;             for (int r = 0; r < 16; ++r) { pe[r] = __builtin_amdgcn_exp2f(sc[r]); lsum += pe[r]; }
;             u32x4 pw0, pw1;
;             pw0.x = cvtpk(pe[0], pe[1]); pw0.y = cvtpk(pe[2], pe[3]); pw0.z = cvtpk(pe[4], pe[5]); pw0.w = cvtpk(pe[6], pe[7]);
;             pw1.x = cvtpk(pe[8], pe[9]); pw1.y = cvtpk(pe[10], pe[11]); pw1.z = cvtpk(pe[12], pe[13]); pw1.w = cvtpk(pe[14], pe[15]);
;             VTRW(8, va, pw0, pw1);
;             const bf16x8 pa0 = __builtin_bit_cast(bf16x8, pw0), pa1 = __builtin_bit_cast(bf16x8, pw1);
;             o[0] = __builtin_amdgcn_mfma_f32_32x32x16_bf16(pa0, VFR2(va[0], va[1]), o[0], 0, 0, 0); o[0] = __builtin_amdgcn_mfma_f32_32x32x16_bf16(pa1, VFR2(va[2], va[3]), o[0], 0, 0, 0);
;             o[1] = __builtin_amdgcn_mfma_f32_32x32x16_bf16(pa0, VFR2(va[4], va[5]), o[1], 0, 0, 0); o[1] = __builtin_amdgcn_mfma_f32_32x32x16_bf16(pa1, VFR2(va[6], va[7]), o[1], 0, 0, 0);
;             VTRW(0, vb, pw0, pw1);
;             o[2] = __builtin_amdgcn_mfma_f32_32x32x16_bf16(pa0, VFR2(vb[0], vb[1]), o[2], 0, 0, 0); o[2] = __builtin_amdgcn_mfma_f32_32x32x16_bf16(pa1, VFR2(vb[2], vb[3]), o[2], 0, 0, 0);
;             o[3] = __builtin_amdgcn_mfma_f32_32x32x16_bf16(pa0, VFR2(vb[4], vb[5]), o[3], 0, 0, 0); o[3] = __builtin_amdgcn_mfma_f32_32x32x16_bf16(pa1, VFR2(vb[6], vb[7]), o[3], 0, 0, 0);
;         }
;         asm volatile("s_waitcnt vmcnt(0) lgkmcnt(0)" ::: "memory"); __builtin_amdgcn_s_barrier(); asm volatile("" ::: "memory");
.Lp6_wd:
	s_barrier
	s_add_u32 s38, s38, 0x10000
	s_addc_u32 s39, s39, 0
	s_cmp_eq_u32 s38, 0x70000
	s_cbranch_scc1 .LBB0_974
	s_mov_b32 s47, s46
	s_branch .LBB0_970
.LBB0_974:
	s_and_b64 vcc, exec, s[4:5]
	s_cbranch_vccnz .LBB0_976
	v_add_u32_e32 v235, 0x10000, v197
	v_add_u32_e32 v16, 0x10000, v190
	v_add_u32_e32 v30, 0x10000, v191
	v_add_u32_e32 v31, 0x10000, v192
	v_add_u32_e32 v183, 0x10000, v193
	v_add_u32_e32 v184, 0x10000, v194
	v_add_u32_e32 v185, 0x10000, v195
	v_add_u32_e32 v234, 0x10000, v196
	ds_read_b128 v[18:21], v235 offset:32768
	ds_read_b128 v[22:25], v234 offset:32768
	ds_read_b128 v[26:29], v185 offset:32768
	ds_read_b128 v[214:217], v184 offset:32768
	ds_read_b128 v[218:221], v183 offset:32768
	ds_read_b128 v[222:225], v31 offset:32768
	ds_read_b128 v[226:229], v30 offset:32768
	ds_read_b128 v[230:233], v16 offset:32768
	s_waitcnt lgkmcnt(0)
	s_waitcnt lgkmcnt(0)
	s_nop 0
	v_mfma_f32_32x32x16_bf16 v[96:111], v[230:233], v[112:115], v[0:15]
	s_add_i32 s4, s45, 0
	s_add_i32 s4, s4, 0x1c000
	v_mfma_f32_32x32x16_bf16 v[96:111], v[226:229], v[116:119], v[96:111]
	v_mfma_f32_32x32x16_bf16 v[96:111], v[222:225], v[120:123], v[96:111]
	v_mfma_f32_32x32x16_bf16 v[96:111], v[218:221], v[128:131], v[96:111]
	v_mfma_f32_32x32x16_bf16 v[96:111], v[214:217], v[136:139], v[96:111]
	v_mfma_f32_32x32x16_bf16 v[96:111], v[26:29], v[152:155], v[96:111]
	v_mfma_f32_32x32x16_bf16 v[96:111], v[22:25], v[164:167], v[96:111]
	ds_read_b128 v[22:25], v235 offset:40960
	ds_read_b128 v[26:29], v234 offset:40960
	ds_read_b128 v[112:115], v185 offset:40960
	ds_read_b128 v[116:119], v184 offset:40960
	ds_read_b128 v[120:123], v183 offset:40960
	ds_read_b128 v[128:131], v31 offset:40960
	v_add_u32_e32 v31, s4, v200
	v_mfma_f32_32x32x16_bf16 v[96:111], v[18:21], v[148:151], v[96:111]
	ds_read_b128 v[18:21], v30 offset:40960
	ds_read_b128 v[136:139], v16 offset:40960
	s_waitcnt lgkmcnt(0)
	s_waitcnt lgkmcnt(0)
	v_add_u32_e32 v16, s4, v199
	v_mfma_f32_32x32x16_bf16 v[96:111], v[136:139], v[124:127], v[96:111]
	v_add_u32_e32 v30, s4, v203
	v_add_u32_e32 v136, s4, v201
	v_add_u32_e32 v137, s4, v205
	v_add_u32_e32 v138, s4, v202
	v_add_u32_e32 v139, s4, v206
	v_mfma_f32_32x32x16_bf16 v[96:111], v[18:21], v[132:135], v[96:111]
	v_mfma_f32_32x32x16_bf16 v[96:111], v[128:131], v[140:143], v[96:111]
	v_mfma_f32_32x32x16_bf16 v[96:111], v[120:123], v[156:159], v[96:111]
	v_add_u32_e32 v120, s4, v204
	v_mfma_f32_32x32x16_bf16 v[96:111], v[116:119], v[168:171], v[96:111]
	v_mfma_f32_32x32x16_bf16 v[96:111], v[112:115], v[172:175], v[96:111]
	v_mfma_f32_32x32x16_bf16 v[96:111], v[26:29], v[160:163], v[96:111]
	ds_read_b64_tr_b16 v[116:117], v16
	ds_read_b64_tr_b16 v[118:119], v30
	ds_read_b64_tr_b16 v[112:113], v16 offset:4096
	ds_read_b64_tr_b16 v[114:115], v30 offset:4096
	ds_read_b64_tr_b16 v[26:27], v31
	ds_read_b64_tr_b16 v[28:29], v120
	ds_read_b64_tr_b16 v[18:19], v31 offset:4096
	ds_read_b64_tr_b16 v[20:21], v120 offset:4096
	ds_read_b64_tr_b16 v[132:133], v136
	ds_read_b64_tr_b16 v[134:135], v137
	ds_read_b64_tr_b16 v[128:129], v136 offset:4096
	ds_read_b64_tr_b16 v[130:131], v137 offset:4096
	ds_read_b64_tr_b16 v[124:125], v138
	ds_read_b64_tr_b16 v[126:127], v139
	ds_read_b64_tr_b16 v[120:121], v138 offset:4096
	ds_read_b64_tr_b16 v[122:123], v139 offset:4096
	v_mfma_f32_32x32x16_bf16 v[96:111], v[22:25], v[144:147], v[96:111]
	s_nop 11
	v_exp_f32_e32 v16, v96
	v_exp_f32_e32 v30, v97
	v_exp_f32_e32 v31, v98
	v_exp_f32_e32 v136, v99
	v_exp_f32_e32 v100, v100
	v_exp_f32_e32 v101, v101
	v_exp_f32_e32 v102, v102
	v_exp_f32_e32 v103, v103
	v_exp_f32_e32 v104, v104
	v_exp_f32_e32 v105, v105
	v_exp_f32_e32 v106, v106
	v_exp_f32_e32 v107, v107
	v_exp_f32_e32 v108, v108
	v_exp_f32_e32 v109, v109
	v_exp_f32_e32 v110, v110
	v_exp_f32_e32 v111, v111
	v_cvt_pk_bf16_f32 v22, v16, v30
	v_cvt_pk_bf16_f32 v23, v31, v136
	v_cvt_pk_bf16_f32 v24, v100, v101
	v_cvt_pk_bf16_f32 v25, v102, v103
	v_cvt_pk_bf16_f32 v96, v104, v105
	v_cvt_pk_bf16_f32 v97, v106, v107
	v_cvt_pk_bf16_f32 v98, v108, v109
	v_cvt_pk_bf16_f32 v99, v110, v111
	s_waitcnt lgkmcnt(8)
	v_add_f32_e32 v16, v181, v16
	v_mfma_f32_32x32x16_bf16 v[64:79], v[22:25], v[26:29], v[64:79]
	v_mov_b64_e32 v[28:29], v[24:25]
	v_mov_b64_e32 v[26:27], v[22:23]
	v_add_f32_e32 v16, v30, v16
	v_add_f32_e32 v16, v31, v16
	v_add_f32_e32 v16, v136, v16
	v_add_f32_e32 v16, v100, v16
	v_add_f32_e32 v16, v101, v16
	v_mfma_f32_32x32x16_bf16 v[64:79], v[96:99], v[18:21], v[64:79]
	v_mov_b64_e32 v[18:19], v[96:97]
	v_mov_b64_e32 v[20:21], v[98:99]
	s_waitcnt lgkmcnt(0)
	v_add_f32_e32 v16, v102, v16
	v_add_f32_e32 v16, v103, v16
	v_add_f32_e32 v16, v104, v16
	v_add_f32_e32 v16, v105, v16
	v_mfma_f32_32x32x16_bf16 v[80:95], v[22:25], v[116:119], v[80:95]
	v_add_f32_e32 v16, v106, v16
	v_add_f32_e32 v16, v107, v16
	v_add_f32_e32 v16, v108, v16
	v_add_f32_e32 v16, v109, v16
	v_add_f32_e32 v16, v110, v16
	v_add_f32_e32 v181, v111, v16
	v_mfma_f32_32x32x16_bf16 v[48:63], v[22:25], v[132:135], v[48:63]
	v_mfma_f32_32x32x16_bf16 v[32:47], v[22:25], v[124:127], v[32:47]
	v_mfma_f32_32x32x16_bf16 v[80:95], v[96:99], v[112:115], v[80:95]
	v_mfma_f32_32x32x16_bf16 v[48:63], v[96:99], v[128:131], v[48:63]
	v_mfma_f32_32x32x16_bf16 v[32:47], v[96:99], v[120:123], v[32:47]

; #define LAS __attribute__((address_space(3)))
; __global__ void __launch_bounds__(512, 2) fwd_kernel(Args a) {
;     extern __shared__ __attribute__((aligned(16))) unsigned char lds_raw[];
;     LAS unsigned char* lds = (LAS unsigned char*)lds_raw;
;     cg::grid_group grid = cg::this_grid();
;     const int tid = threadIdx.x, lane = tid & 63, wave = __builtin_amdgcn_readfirstlane(tid >> 6);
	.amdhsa_kernel _Z10fwd_kernel4Args
		.amdhsa_group_segment_fixed_size 0
		.amdhsa_private_segment_fixed_size 0
		.amdhsa_kernarg_size 528
		.amdhsa_user_sgpr_count 2
		.amdhsa_user_sgpr_dispatch_ptr 0
		.amdhsa_user_sgpr_queue_ptr 0
		.amdhsa_user_sgpr_kernarg_segment_ptr 1
		.amdhsa_user_sgpr_dispatch_id 0
		.amdhsa_user_sgpr_kernarg_preload_length 0
		.amdhsa_user_sgpr_kernarg_preload_offset 0
		.amdhsa_user_sgpr_private_segment_size 0
		.amdhsa_uses_dynamic_stack 0
		.amdhsa_enable_private_segment 0
		.amdhsa_system_sgpr_workgroup_id_x 1
		.amdhsa_system_sgpr_workgroup_id_y 0
		.amdhsa_system_sgpr_workgroup_id_z 0
		.amdhsa_system_sgpr_workgroup_info 0
		.amdhsa_system_vgpr_workitem_id 2
		.amdhsa_next_free_vgpr 256
		.amdhsa_next_free_sgpr 102
		.amdhsa_accum_offset 256
		.amdhsa_reserve_vcc 1
		.amdhsa_float_round_mode_32 0
		.amdhsa_float_round_mode_16_64 0
		.amdhsa_float_denorm_mode_32 3
		.amdhsa_float_denorm_mode_16_64 3
		.amdhsa_dx10_clamp 1
		.amdhsa_ieee_mode 1
		.amdhsa_fp16_overflow 0
		.amdhsa_tg_split 0
		.amdhsa_exception_fp_ieee_invalid_op 0
		.amdhsa_exception_fp_denorm_src 0
		.amdhsa_exception_fp_ieee_div_zero 0
		.amdhsa_exception_fp_ieee_overflow 0
		.amdhsa_exception_fp_ieee_underflow 0
		.amdhsa_exception_fp_ieee_inexact 0
		.amdhsa_exception_int_div_zero 0
	.end_amdhsa_kernel

; __global__ void __launch_bounds__(512, 2) fwd_kernel(Args a) {
amdhsa.kernels:
  - .agpr_count:     0
    .args:
      - .offset:         0
        .size:           272
        .value_kind:     by_value
      - .offset:         272
        .size:           4
        .value_kind:     hidden_block_count_x
      - .offset:         276
        .size:           4
        .value_kind:     hidden_block_count_y
      - .offset:         280
        .size:           4
        .value_kind:     hidden_block_count_z
      - .offset:         284
        .size:           2
        .value_kind:     hidden_group_size_x
      - .offset:         286
        .size:           2
        .value_kind:     hidden_group_size_y
      - .offset:         288
        .size:           2
        .value_kind:     hidden_group_size_z
      - .offset:         290
        .size:           2
        .value_kind:     hidden_remainder_x
      - .offset:         292
        .size:           2
        .value_kind:     hidden_remainder_y
      - .offset:         294
        .size:           2
        .value_kind:     hidden_remainder_z
      - .offset:         312
        .size:           8
        .value_kind:     hidden_global_offset_x
      - .offset:         320
        .size:           8
        .value_kind:     hidden_global_offset_y
      - .offset:         328
        .size:           8
        .value_kind:     hidden_global_offset_z
      - .offset:         336
        .size:           2
        .value_kind:     hidden_grid_dims
      - .offset:         360
        .size:           8
        .value_kind:     hidden_multigrid_sync_arg
      - .offset:         392
        .size:           4
        .value_kind:     hidden_dynamic_lds_size
    .group_segment_fixed_size: 0
    .kernarg_segment_align: 8
    .kernarg_segment_size: 528
    .language:       OpenCL C
    .language_version:
      - 2
      - 0
    .max_flat_workgroup_size: 512
    .name:           _Z10fwd_kernel4Args
    .private_segment_fixed_size: 0
    .sgpr_count:     108
    .sgpr_spill_count: 126
    .symbol:         _Z10fwd_kernel4Args.kd
    .uniform_work_group_size: 1
    .uses_dynamic_stack: false
    .vgpr_count:     256
    .vgpr_spill_count: 0
    .wavefront_size: 64
